# also 64-byte-align the cross-attention kt-loop and SB inner-loop headers
# speedup vs baseline: 1.0069x; 1.0010x over previous
; __device__ __forceinline__ u32x4 pack8(const float* f) { u32x4 o; o.x = pk2(f[0], f[1]); o.y = pk2(f[2], f[3]); o.z = pk2(f[4], f[5]); o.w = pk2(f[6], f[7]); return o; }
; __device__ __forceinline__ void phase_xattn(CArgs& A, int l, unsigned char* lds, int tid) {
;     ...
;         const int wave = tid >> 6, lane = tid & 63, r = lane & 15, g = lane >> 4;
;         const int b = it >> 6, h = (it >> 4) & 3, qch = it & 15;
;         const size_t row = (size_t)b * SEQ + qch * 128 + wave * 16 + r;
;         bf16x8 qf[8];
; #pragma unroll
;         for (int ks = 0; ks < 8; ++ks) { float f[8]; unpack8(*(const u32x4*)(Q + row * DM + h * 256 + 32 * ks + 8 * g), f);
; #pragma unroll
;             for (int i = 0; i < 8; ++i) f[i] *= 0.0625f;
;             qf[ks] = __builtin_bit_cast(bf16x8, pack8(f)); }
;         f32x4 o[16];
; #pragma unroll
;         for (int i = 0; i < 16; ++i) o[i] = (f32x4){0.f, 0.f, 0.f, 0.f};
;         float m = -INFINITY, lsum = 0.f;
;         const int skey = tid >> 3, sdc = (tid & 7) * 32;
;         const bf16* kvbase = KV + ((size_t)b * NMEM + skey) * 4096 + l * 2048 + h * 256 + sdc;
;         u32x4 kr[4], vr[4];
; #pragma unroll
;         for (int i = 0; i < 4; ++i) { kr[i] = *(const u32x4*)(kvbase + i * 8); vr[i] = *(const u32x4*)(kvbase + 1024 + i * 8); }
.LBB0_144:
	s_ashr_i32 s4, s11, 6
	s_ashr_i32 s5, s4, 31
	s_lshl_b32 s8, s11, 7
	s_lshl_b64 s[0:1], s[4:5], 11
	s_and_b32 s8, s8, 0x780
	v_ashrrev_i32_e32 v2, 2, v1
	v_and_b32_e32 v36, 15, v1
	s_or_b32 s0, s0, s8
	v_and_b32_e32 v2, -16, v2
	v_ashrrev_i32_e32 v3, 31, v2
	v_or_b32_e32 v4, s0, v36
	v_mov_b32_e32 v5, s1
	v_lshl_add_u64 v[2:3], v[4:5], 0, v[2:3]
	s_lshl_b32 s0, s11, 4
	v_lshlrev_b64 v[144:145], 11, v[2:3]
	s_and_b32 s36, s0, 0x300
	v_bfe_u32 v37, v1, 4, 2
	v_lshl_add_u64 v[2:3], s[38:39], 0, v[144:145]
	s_lshl_b32 s14, s36, 1
	v_lshl_add_u64 v[2:3], v[2:3], 0, s[14:15]
	v_lshlrev_b32_e32 v34, 4, v37
	v_mov_b32_e32 v35, v0
	v_lshl_add_u64 v[22:23], v[2:3], 0, v[34:35]
	v_ashrrev_i32_e32 v204, 3, v1
	s_lshl_b64 s[98:99], s[4:5], 21
	v_ashrrev_i32_e32 v205, 31, v204
	s_add_u32 s98, s9, s98
	s_addc_u32 s99, s10, s99
	v_lshlrev_b64 v[206:207], 13, v[204:205]
	v_lshl_add_u64 v[208:209], s[98:99], 0, v[206:207]
	v_lshl_add_u64 v[208:209], s[40:41], 1, v[208:209]
	v_lshlrev_b32_e32 v206, 6, v1
	v_lshl_add_u64 v[208:209], v[208:209], 0, s[14:15]
	v_and_b32_e32 v206, 0x1c0, v206
	v_mov_b32_e32 v207, v0
	v_lshl_add_u64 v[208:209], v[208:209], 0, v[206:207]
	global_load_dwordx4 v[102:105], v[208:209], off offset:32
	global_load_dwordx4 v[106:109], v[208:209], off offset:16
	global_load_dwordx4 v[110:113], v[208:209], off
	global_load_dwordx4 v[114:117], v[208:209], off offset:2096
	global_load_dwordx4 v[118:121], v[208:209], off offset:2080
	global_load_dwordx4 v[122:125], v[208:209], off offset:2064
	global_load_dwordx4 v[126:129], v[208:209], off offset:2048
	global_load_dwordx4 v[2:5], v[22:23], off
	global_load_dwordx4 v[6:9], v[22:23], off offset:64
	global_load_dwordx4 v[10:13], v[22:23], off offset:128
	global_load_dwordx4 v[14:17], v[22:23], off offset:192
	global_load_dwordx4 v[18:21], v[22:23], off offset:256
	global_load_dwordx4 v[212:215], v[22:23], off offset:320
	global_load_dwordx4 v[216:219], v[22:23], off offset:384
	global_load_dwordx4 v[220:223], v[22:23], off offset:448
	s_mov_b32 s0, 0x3d800000
	v_mov_b32_e32 v147, v0
	v_cmp_lt_i32_e32 vcc, v178, v173
	v_lshlrev_b32_e32 v143, 2, v37
	v_and_b32_e32 v37, 7, v1
	v_lshlrev_b32_e32 v37, 6, v37
	v_mul_u32_u24_e32 v36, 0x220, v36
	v_mov_b32_e32 v130, 0
	v_mov_b32_e32 v156, 0xff800000
	s_mov_b64 s[44:45], 0
	v_mov_b32_e32 v51, v130
	s_waitcnt lgkmcnt(0)
	v_mov_b32_e32 v52, v130
	s_waitcnt lgkmcnt(2)
	v_mov_b32_e32 v53, v130
	v_mov_b32_e32 v54, 0
	v_mov_b32_e32 v55, v130
	s_waitcnt lgkmcnt(1)
	v_mov_b32_e32 v56, v130
	s_waitcnt lgkmcnt(0)
	v_mov_b32_e32 v57, v130
	v_mov_b32_e32 v58, 0
	v_mov_b32_e32 v59, v130
	v_mov_b32_e32 v60, v130
	v_mov_b32_e32 v61, v130
	v_mov_b32_e32 v74, 0
	v_mov_b32_e32 v75, v130
	v_mov_b32_e32 v76, v130
	v_mov_b32_e32 v77, v130
	s_waitcnt vmcnt(0)
	v_mov_b32_e32 v94, 0
	v_mov_b32_e32 v95, v130
	v_mov_b32_e32 v96, v130
	v_mov_b32_e32 v97, v130
	v_mov_b32_e32 v82, 0
	v_mov_b32_e32 v83, v130
	v_mov_b32_e32 v84, v130
	v_mov_b32_e32 v85, v130
	v_mov_b32_e32 v90, 0
	v_mov_b32_e32 v91, v130
	v_mov_b32_e32 v92, v130
	v_mov_b32_e32 v93, v130
	v_mov_b32_e32 v78, 0
	v_mov_b32_e32 v79, v130
	v_mov_b32_e32 v80, v130
	v_mov_b32_e32 v81, v130
	v_mov_b32_e32 v70, 0
	v_mov_b32_e32 v71, v130
	v_mov_b32_e32 v72, v130
	v_mov_b32_e32 v73, v130
	v_mov_b32_e32 v62, 0
	v_mov_b32_e32 v63, v130
	v_mov_b32_e32 v64, v130
	v_mov_b32_e32 v65, v130
	v_mov_b32_e32 v66, 0
	v_mov_b32_e32 v67, v130
	v_mov_b32_e32 v68, v130
	v_mov_b32_e32 v69, v130
	v_mov_b32_e32 v86, 0
	v_mov_b32_e32 v87, v130
	v_mov_b32_e32 v88, v130
	v_mov_b32_e32 v89, v130
	s_waitcnt vmcnt(4)
	v_lshlrev_b32_e32 v25, 16, v3
	v_lshlrev_b32_e32 v24, 16, v2
	v_and_b32_e32 v3, 0xffff0000, v3
	v_and_b32_e32 v2, 0xffff0000, v2
	v_lshlrev_b32_e32 v27, 16, v5
	v_lshlrev_b32_e32 v26, 16, v4
	v_and_b32_e32 v5, 0xffff0000, v5
	v_and_b32_e32 v4, 0xffff0000, v4
	s_waitcnt vmcnt(3)
	v_lshlrev_b32_e32 v29, 16, v7
	v_lshlrev_b32_e32 v28, 16, v6
	v_and_b32_e32 v7, 0xffff0000, v7
	v_and_b32_e32 v6, 0xffff0000, v6
	v_lshlrev_b32_e32 v31, 16, v9
	v_lshlrev_b32_e32 v30, 16, v8
	v_and_b32_e32 v9, 0xffff0000, v9
	v_and_b32_e32 v8, 0xffff0000, v8
	v_pk_mul_f32 v[24:25], v[24:25], s[0:1] op_sel_hi:[1,0]
	v_pk_mul_f32 v[2:3], v[2:3], s[0:1] op_sel_hi:[1,0]
	v_pk_mul_f32 v[26:27], v[26:27], s[0:1] op_sel_hi:[1,0]
	v_pk_mul_f32 v[4:5], v[4:5], s[0:1] op_sel_hi:[1,0]
	v_pk_mul_f32 v[28:29], v[28:29], s[0:1] op_sel_hi:[1,0]
	v_pk_mul_f32 v[6:7], v[6:7], s[0:1] op_sel_hi:[1,0]
	v_pk_mul_f32 v[30:31], v[30:31], s[0:1] op_sel_hi:[1,0]
	v_pk_mul_f32 v[8:9], v[8:9], s[0:1] op_sel_hi:[1,0]
	v_bfe_u32 v39, v24, 16, 1
	v_bfe_u32 v32, v5, 16, 1
	v_bfe_u32 v35, v3, 16, 1
	v_bfe_u32 v38, v2, 16, 1
	v_bfe_u32 v40, v25, 16, 1
	v_bfe_u32 v41, v26, 16, 1
	v_bfe_u32 v42, v27, 16, 1
	v_bfe_u32 v44, v8, 16, 1
	v_bfe_u32 v46, v6, 16, 1
	v_bfe_u32 v47, v28, 16, 1
	v_bfe_u32 v49, v30, 16, 1
	v_bfe_u32 v50, v31, 16, 1
	v_add3_u32 v24, v24, v39, s84
	v_bfe_u32 v33, v4, 16, 1
	v_bfe_u32 v43, v9, 16, 1
	v_bfe_u32 v45, v7, 16, 1
	v_bfe_u32 v48, v29, 16, 1
	v_add3_u32 v2, v2, v38, s84
	v_add3_u32 v3, v3, v35, s84
	v_add3_u32 v5, v5, v32, s84
	v_add3_u32 v27, v27, v42, s84
	v_add3_u32 v26, v26, v41, s84
	v_add3_u32 v25, v25, v40, s84
	v_add3_u32 v32, v6, v46, s84
	v_add3_u32 v35, v8, v44, s84
	v_add3_u32 v31, v31, v50, s84
	v_add3_u32 v6, v30, v49, s84
	v_add3_u32 v8, v28, v47, s84
	v_lshrrev_b32_e32 v24, 16, v24
	v_add3_u32 v4, v4, v33, s84
	v_add3_u32 v33, v7, v45, s84
	v_add3_u32 v38, v9, v43, s84
	v_add3_u32 v7, v29, v48, s84
	v_lshrrev_b32_e32 v25, 16, v25
	v_lshrrev_b32_e32 v26, 16, v26
	v_lshrrev_b32_e32 v9, 16, v27
	v_lshrrev_b32_e32 v27, 16, v8
	v_lshrrev_b32_e32 v29, 16, v6
	v_and_or_b32 v6, v2, s3, v24
	v_lshrrev_b32_e32 v2, 16, v31
	v_lshrrev_b32_e32 v28, 16, v7
	v_and_or_b32 v9, v5, s3, v9
	v_and_or_b32 v8, v4, s3, v26
	v_and_or_b32 v7, v3, s3, v25
	v_and_or_b32 v5, v38, s3, v2
	v_and_or_b32 v2, v32, s3, v27
	s_waitcnt vmcnt(2)
; __device__ __forceinline__ u32x4 pack8(const float* f) { u32x4 o; o.x = pk2(f[0], f[1]); o.y = pk2(f[2], f[3]); o.z = pk2(f[4], f[5]); o.w = pk2(f[6], f[7]); return o; }
; __device__ __forceinline__ void phase_xattn(CArgs& A, int l, unsigned char* lds, int tid) {
;     ...
;         for (int ks = 0; ks < 8; ++ks) { float f[8]; unpack8(*(const u32x4*)(Q + row * DM + h * 256 + 32 * ks + 8 * g), f);
; #pragma unroll
;             for (int i = 0; i < 8; ++i) f[i] *= 0.0625f;
;             qf[ks] = __builtin_bit_cast(bf16x8, pack8(f)); }
	v_lshlrev_b32_e32 v25, 16, v11
	v_lshlrev_b32_e32 v24, 16, v10
	v_and_b32_e32 v11, 0xffff0000, v11
	v_and_b32_e32 v10, 0xffff0000, v10
	v_lshlrev_b32_e32 v27, 16, v13
	v_lshlrev_b32_e32 v26, 16, v12
	v_and_b32_e32 v13, 0xffff0000, v13
	v_and_b32_e32 v12, 0xffff0000, v12
	v_pk_mul_f32 v[10:11], v[10:11], s[0:1] op_sel_hi:[1,0]
	v_pk_mul_f32 v[12:13], v[12:13], s[0:1] op_sel_hi:[1,0]
	v_and_or_b32 v4, v35, s3, v29
	v_and_or_b32 v3, v33, s3, v28
	v_pk_mul_f32 v[24:25], v[24:25], s[0:1] op_sel_hi:[1,0]
	v_pk_mul_f32 v[26:27], v[26:27], s[0:1] op_sel_hi:[1,0]
	v_bfe_u32 v28, v13, 16, 1
	v_bfe_u32 v29, v12, 16, 1
	v_bfe_u32 v30, v11, 16, 1
	v_bfe_u32 v31, v10, 16, 1
	v_add3_u32 v10, v10, v31, s84
	v_add3_u32 v11, v11, v30, s84
	v_add3_u32 v12, v12, v29, s84
	v_add3_u32 v13, v13, v28, s84
	v_bfe_u32 v28, v24, 16, 1
	v_bfe_u32 v29, v25, 16, 1
	v_bfe_u32 v30, v26, 16, 1
	v_bfe_u32 v31, v27, 16, 1
	v_add3_u32 v31, v27, v31, s84
	v_add3_u32 v26, v26, v30, s84
	v_add3_u32 v25, v25, v29, s84
	v_add3_u32 v24, v24, v28, s84
	v_lshrrev_b32_e32 v28, 16, v24
	v_lshrrev_b32_e32 v29, 16, v25
	v_lshrrev_b32_e32 v30, 16, v26
	v_mov_b32_e32 v24, v212
	v_mov_b32_e32 v25, v213
	v_mov_b32_e32 v26, v214
	v_mov_b32_e32 v27, v215
	v_lshrrev_b32_e32 v31, 16, v31
	v_and_or_b32 v13, v13, s3, v31
	v_and_or_b32 v12, v12, s3, v30
	s_waitcnt vmcnt(2)
	v_lshlrev_b32_e32 v31, 16, v17
	v_lshlrev_b32_e32 v30, 16, v16
	v_and_b32_e32 v17, 0xffff0000, v17
	v_and_b32_e32 v16, 0xffff0000, v16
	v_and_or_b32 v11, v11, s3, v29
	v_and_or_b32 v10, v10, s3, v28
	v_lshlrev_b32_e32 v29, 16, v15
	v_lshlrev_b32_e32 v28, 16, v14
	v_and_b32_e32 v15, 0xffff0000, v15
	v_and_b32_e32 v14, 0xffff0000, v14
	v_pk_mul_f32 v[16:17], v[16:17], s[0:1] op_sel_hi:[1,0]
	v_pk_mul_f32 v[28:29], v[28:29], s[0:1] op_sel_hi:[1,0]
	v_pk_mul_f32 v[14:15], v[14:15], s[0:1] op_sel_hi:[1,0]
	v_bfe_u32 v32, v17, 16, 1
	v_bfe_u32 v33, v16, 16, 1
	v_pk_mul_f32 v[30:31], v[30:31], s[0:1] op_sel_hi:[1,0]
	v_bfe_u32 v35, v15, 16, 1
	v_bfe_u32 v38, v14, 16, 1
	v_add3_u32 v16, v16, v33, s84
	v_add3_u32 v17, v17, v32, s84
	v_bfe_u32 v32, v28, 16, 1
	v_bfe_u32 v33, v29, 16, 1
	v_add3_u32 v14, v14, v38, s84
	v_add3_u32 v15, v15, v35, s84
	v_bfe_u32 v35, v30, 16, 1
	v_bfe_u32 v38, v31, 16, 1
	v_add3_u32 v29, v29, v33, s84
	v_add3_u32 v28, v28, v32, s84
	v_add3_u32 v38, v31, v38, s84
	v_add3_u32 v35, v30, v35, s84
	v_lshrrev_b32_e32 v32, 16, v28
	v_lshrrev_b32_e32 v33, 16, v29
	v_mov_b32_e32 v28, v216
	v_mov_b32_e32 v29, v217
	v_mov_b32_e32 v30, v218
	v_mov_b32_e32 v31, v219
	v_lshrrev_b32_e32 v38, 16, v38
	v_and_or_b32 v17, v17, s3, v38
	v_and_or_b32 v15, v15, s3, v33
	v_and_or_b32 v14, v14, s3, v32
	s_waitcnt vmcnt(2)
	v_lshlrev_b32_e32 v33, 16, v19
	v_lshlrev_b32_e32 v32, 16, v18
	v_and_b32_e32 v19, 0xffff0000, v19
	v_and_b32_e32 v18, 0xffff0000, v18
	v_lshlrev_b32_e32 v39, 16, v21
	v_lshlrev_b32_e32 v38, 16, v20
	v_and_b32_e32 v21, 0xffff0000, v21
	v_and_b32_e32 v20, 0xffff0000, v20
	v_pk_mul_f32 v[18:19], v[18:19], s[0:1] op_sel_hi:[1,0]
	v_pk_mul_f32 v[20:21], v[20:21], s[0:1] op_sel_hi:[1,0]
	v_pk_mul_f32 v[32:33], v[32:33], s[0:1] op_sel_hi:[1,0]
	v_pk_mul_f32 v[38:39], v[38:39], s[0:1] op_sel_hi:[1,0]
	v_bfe_u32 v40, v20, 16, 1
	v_bfe_u32 v41, v19, 16, 1
	v_bfe_u32 v42, v18, 16, 1
	v_add3_u32 v18, v18, v42, s84
	v_add3_u32 v19, v19, v41, s84
	v_add3_u32 v20, v20, v40, s84
	v_bfe_u32 v40, v33, 16, 1
	v_bfe_u32 v41, v38, 16, 1
	v_bfe_u32 v42, v39, 16, 1
	v_add3_u32 v42, v39, v42, s84
	v_add3_u32 v43, v38, v41, s84
	v_add3_u32 v33, v33, v40, s84
	v_mov_b32_e32 v38, v220
	v_mov_b32_e32 v39, v221
	v_mov_b32_e32 v40, v222
	v_mov_b32_e32 v41, v223
	v_lshrrev_b32_e32 v35, 16, v35
	v_and_or_b32 v16, v16, s3, v35
	v_bfe_u32 v35, v21, 16, 1
	v_add3_u32 v21, v21, v35, s84
	v_bfe_u32 v35, v32, 16, 1
	v_add3_u32 v32, v32, v35, s84
	v_lshrrev_b32_e32 v32, 16, v32
	v_lshrrev_b32_e32 v22, 16, v33
	v_lshrrev_b32_e32 v23, 16, v43
	v_lshrrev_b32_e32 v33, 16, v42
	v_and_or_b32 v21, v21, s3, v33
	v_and_or_b32 v20, v20, s3, v23
	v_and_or_b32 v19, v19, s3, v22
	v_and_or_b32 v18, v18, s3, v32
	s_waitcnt vmcnt(2)
	v_lshlrev_b32_e32 v23, 16, v25
	v_lshlrev_b32_e32 v22, 16, v24
	v_and_b32_e32 v25, 0xffff0000, v25
	v_and_b32_e32 v24, 0xffff0000, v24
	v_lshlrev_b32_e32 v33, 16, v27
	v_lshlrev_b32_e32 v32, 16, v26
	v_and_b32_e32 v27, 0xffff0000, v27
	v_and_b32_e32 v26, 0xffff0000, v26
	v_pk_mul_f32 v[24:25], v[24:25], s[0:1] op_sel_hi:[1,0]
	v_pk_mul_f32 v[26:27], v[26:27], s[0:1] op_sel_hi:[1,0]
	v_pk_mul_f32 v[32:33], v[32:33], s[0:1] op_sel_hi:[1,0]
	v_bfe_u32 v35, v27, 16, 1
	v_bfe_u32 v42, v26, 16, 1
	v_bfe_u32 v43, v25, 16, 1
	v_bfe_u32 v44, v24, 16, 1
	v_pk_mul_f32 v[22:23], v[22:23], s[0:1] op_sel_hi:[1,0]
	v_add3_u32 v44, v24, v44, s84
	v_add3_u32 v43, v25, v43, s84
	v_add3_u32 v24, v26, v42, s84
	v_add3_u32 v25, v27, v35, s84
	v_bfe_u32 v35, v32, 16, 1
	v_bfe_u32 v42, v33, 16, 1
	v_bfe_u32 v26, v22, 16, 1
	v_bfe_u32 v27, v23, 16, 1
	v_add3_u32 v33, v33, v42, s84
	v_add3_u32 v32, v32, v35, s84
	v_add3_u32 v23, v23, v27, s84
	v_add3_u32 v22, v22, v26, s84
	v_lshrrev_b32_e32 v26, 16, v32
	v_lshrrev_b32_e32 v27, 16, v33
	v_and_or_b32 v25, v25, s3, v27
	v_and_or_b32 v24, v24, s3, v26
	v_lshrrev_b32_e32 v22, 16, v22
	v_lshrrev_b32_e32 v23, 16, v23
	v_and_or_b32 v23, v43, s3, v23
	v_and_or_b32 v22, v44, s3, v22
	s_waitcnt vmcnt(1)
; __device__ __forceinline__ u32x4 pack8(const float* f) { u32x4 o; o.x = pk2(f[0], f[1]); o.y = pk2(f[2], f[3]); o.z = pk2(f[4], f[5]); o.w = pk2(f[6], f[7]); return o; }
; __device__ __forceinline__ void phase_xattn(CArgs& A, int l, unsigned char* lds, int tid) {
;     ...
;         for (int ks = 0; ks < 8; ++ks) { float f[8]; unpack8(*(const u32x4*)(Q + row * DM + h * 256 + 32 * ks + 8 * g), f);
; #pragma unroll
;             for (int i = 0; i < 8; ++i) f[i] *= 0.0625f;
;             qf[ks] = __builtin_bit_cast(bf16x8, pack8(f)); }
;         f32x4 o[16];
; #pragma unroll
;         for (int i = 0; i < 16; ++i) o[i] = (f32x4){0.f, 0.f, 0.f, 0.f};
;         float m = -INFINITY, lsum = 0.f;
;         const int skey = tid >> 3, sdc = (tid & 7) * 32;
;         const bf16* kvbase = KV + ((size_t)b * NMEM + skey) * 4096 + l * 2048 + h * 256 + sdc;
;         u32x4 kr[4], vr[4];
; #pragma unroll
;         for (int i = 0; i < 4; ++i) { kr[i] = *(const u32x4*)(kvbase + i * 8); vr[i] = *(const u32x4*)(kvbase + 1024 + i * 8); }
;         for (int kt = 0; kt < 4; ++kt) {
;             __syncthreads();
; #pragma unroll
;             for (int i = 0; i < 4; ++i) *(u32x4*)(Ks + skey * XA_KP + (sdc + i * 8) * 2) = kr[i];
; #pragma unroll
;             for (int i = 0; i < 4; ++i) *(u32x4*)(Vt + skey * XA_VP + (sdc + i * 8) * 2) = vr[i];
;             __syncthreads();
	v_lshlrev_b32_e32 v27, 16, v29
	v_lshlrev_b32_e32 v26, 16, v28
	v_and_b32_e32 v29, 0xffff0000, v29
	v_and_b32_e32 v28, 0xffff0000, v28
	v_lshlrev_b32_e32 v33, 16, v31
	v_lshlrev_b32_e32 v32, 16, v30
	v_and_b32_e32 v31, 0xffff0000, v31
	v_and_b32_e32 v30, 0xffff0000, v30
	v_pk_mul_f32 v[28:29], v[28:29], s[0:1] op_sel_hi:[1,0]
	v_pk_mul_f32 v[30:31], v[30:31], s[0:1] op_sel_hi:[1,0]
	v_pk_mul_f32 v[32:33], v[32:33], s[0:1] op_sel_hi:[1,0]
	v_bfe_u32 v35, v31, 16, 1
	v_bfe_u32 v42, v30, 16, 1
	v_bfe_u32 v43, v29, 16, 1
	v_bfe_u32 v44, v28, 16, 1
	v_pk_mul_f32 v[26:27], v[26:27], s[0:1] op_sel_hi:[1,0]
	v_add3_u32 v44, v28, v44, s84
	v_add3_u32 v43, v29, v43, s84
	v_add3_u32 v28, v30, v42, s84
	v_add3_u32 v29, v31, v35, s84
	v_bfe_u32 v35, v32, 16, 1
	v_bfe_u32 v42, v33, 16, 1
	v_bfe_u32 v30, v26, 16, 1
	v_bfe_u32 v31, v27, 16, 1
	v_add3_u32 v33, v33, v42, s84
	v_add3_u32 v32, v32, v35, s84
	v_add3_u32 v27, v27, v31, s84
	v_add3_u32 v26, v26, v30, s84
	v_lshrrev_b32_e32 v30, 16, v32
	v_lshrrev_b32_e32 v31, 16, v33
	v_and_or_b32 v29, v29, s3, v31
	v_and_or_b32 v28, v28, s3, v30
	s_waitcnt vmcnt(0)
	v_lshlrev_b32_e32 v31, 16, v39
	v_lshlrev_b32_e32 v30, 16, v38
	v_and_b32_e32 v33, 0xffff0000, v39
	v_and_b32_e32 v32, 0xffff0000, v38
	v_lshlrev_b32_e32 v39, 16, v41
	v_lshlrev_b32_e32 v38, 16, v40
	v_and_b32_e32 v41, 0xffff0000, v41
	v_and_b32_e32 v40, 0xffff0000, v40
	v_lshrrev_b32_e32 v26, 16, v26
	v_lshrrev_b32_e32 v27, 16, v27
	v_pk_mul_f32 v[32:33], v[32:33], s[0:1] op_sel_hi:[1,0]
	v_pk_mul_f32 v[40:41], v[40:41], s[0:1] op_sel_hi:[1,0]
	v_and_or_b32 v27, v43, s3, v27
	v_and_or_b32 v26, v44, s3, v26
	v_pk_mul_f32 v[38:39], v[38:39], s[0:1] op_sel_hi:[1,0]
	v_bfe_u32 v35, v41, 16, 1
	v_bfe_u32 v42, v40, 16, 1
	v_bfe_u32 v43, v33, 16, 1
	v_bfe_u32 v44, v32, 16, 1
	v_pk_mul_f32 v[30:31], v[30:31], s[0:1] op_sel_hi:[1,0]
	v_add3_u32 v44, v32, v44, s84
	v_add3_u32 v43, v33, v43, s84
	v_add3_u32 v32, v40, v42, s84
	v_add3_u32 v33, v41, v35, s84
	v_bfe_u32 v41, v38, 16, 1
	v_bfe_u32 v42, v39, 16, 1
	v_bfe_u32 v35, v30, 16, 1
	v_add3_u32 v39, v39, v42, s84
	v_add3_u32 v38, v38, v41, s84
	v_add3_u32 v30, v30, v35, s84
	v_lshrrev_b32_e32 v35, 16, v38
	v_lshrrev_b32_e32 v38, 16, v39
	v_bfe_u32 v40, v31, 16, 1
	v_and_or_b32 v33, v33, s3, v38
	v_ashrrev_i32_e32 v38, 3, v1
	s_lshl_b64 s[0:1], s[4:5], 21
	v_add3_u32 v31, v31, v40, s84
	v_ashrrev_i32_e32 v39, 31, v38
	s_add_u32 s4, s9, s0
	v_lshrrev_b32_e32 v31, 16, v31
	s_addc_u32 s5, s10, s1
	v_lshlrev_b64 v[40:41], 13, v[38:39]
	v_and_or_b32 v31, v43, s3, v31
	v_lshl_add_u64 v[42:43], s[4:5], 0, v[40:41]
	v_and_or_b32 v32, v32, s3, v35
	v_lshl_add_u64 v[42:43], s[40:41], 1, v[42:43]
	v_lshlrev_b32_e32 v35, 6, v1
	v_lshl_add_u64 v[42:43], v[42:43], 0, s[14:15]
	v_and_b32_e32 v146, 0x1c0, v35
	v_lshl_add_u64 v[42:43], v[42:43], 0, v[146:147]
	global_load_dwordx4 v[98:101], v[42:43], off offset:48
	v_add_u32_e32 v39, 0, v34
	v_cndmask_b32_e32 v34, v167, v178, vcc
	v_cmp_lt_i32_e32 vcc, v179, v173
	s_movk_i32 s4, 0x220
	v_lshlrev_b32_e32 v151, 2, v34
	v_cndmask_b32_e32 v34, v167, v179, vcc
	v_mul_lo_u32 v35, v38, s4
	v_lshlrev_b32_e32 v147, 2, v34
	v_bfe_u32 v34, v1, 2, 2
	v_add_u32_e32 v154, 0, v35
	v_or_b32_e32 v34, v143, v34
	v_lshlrev_b32_e32 v35, 3, v1
	v_and_b32_e32 v35, 24, v35
	v_mul_u32_u24_e32 v34, 0x220, v34
	v_add3_u32 v152, 0, v35, v34
	v_lshl_add_u64 v[34:35], s[0:1], 0, v[40:41]
	s_lshl_b32 s0, s11, 5
	s_and_b32 s0, s0, 0x600
	v_lshrrev_b32_e32 v30, 16, v30
	v_mov_b32_e32 v38, v154
	v_or3_b32 v34, v34, s0, v37
	v_and_or_b32 v30, v44, s3, v30
	v_lshl_add_u64 v[148:149], s[42:43], 0, v[34:35]
	v_add_u32_e32 v155, v38, v146
	v_add_u32_e32 v153, v39, v36
	v_mov_b32_e32 v34, 0
	v_mov_b32_e32 v35, v130
	v_mov_b32_e32 v36, v130
	v_mov_b32_e32 v37, v130
	v_mov_b32_e32 v38, 0
	v_mov_b32_e32 v39, v130
	v_mov_b32_e32 v40, v130
	v_mov_b32_e32 v41, v130
	v_mov_b32_e32 v42, 0
	v_mov_b32_e32 v43, v130
	v_mov_b32_e32 v44, v130
	v_mov_b32_e32 v45, v130
	v_mov_b32_e32 v46, 0
	v_mov_b32_e32 v47, v130
	v_mov_b32_e32 v48, v130
	v_mov_b32_e32 v49, v130
	v_mov_b32_e32 v50, 0
	s_waitcnt vmcnt(0)
	.p2align	6

; __device__ __forceinline__ u32x4 pack8(const float* f) { u32x4 o; o.x = pk2(f[0], f[1]); o.y = pk2(f[2], f[3]); o.z = pk2(f[4], f[5]); o.w = pk2(f[6], f[7]); return o; }
; template <int MODE>
; __device__ __forceinline__ void attn_unit(const bf16* P, bf16* Y, int b, int h, int qb, unsigned char* lds, int tid) {
;     const int wave = tid >> 6, lane = tid & 63, r = lane & 31, hf = lane >> 5;
;     const int qcol = (MODE == 0 ? PC_FQ : PC_SQ) + h * 64, kcol = (MODE == 0 ? PC_FK : PC_SK) + h * 64, vcol = (MODE == 0 ? PC_FV : PC_SV) + h * 64;
;     const int q0w = qb * 256 + wave * 32, t = q0w + r;
;     const size_t rowq = (size_t)b * SEQ + t;
;     const float* negc2 = (const float*)(lds + AT_NEGC);
;     bf16x8 qf[4];
; #pragma unroll
;     for (int ks = 0; ks < 4; ++ks) { float f[8]; unpack8(*(const u32x4*)(P + rowq * NP + qcol + 16 * ks + 8 * hf), f);
; #pragma unroll
;         for (int i = 0; i < 8; ++i) f[i] *= 0.125f * LOG2E;
;         qf[ks] = __builtin_bit_cast(bf16x8, pack8(f)); }
;     f32x16 o0, o1;
; #pragma unroll
;     for (int i = 0; i < 16; ++i) { o0[i] = 0.f; o1[i] = 0.f; }
;     float m = -INFINITY, lsum = 0.f, carry = 0.f;
;     const float nref = (MODE == 0) ? negc2[qb * 256] : 0.f;
;     bf16x8 tri[2];
; #pragma unroll
;     for (int s2 = 0; s2 < 2; ++s2)
; #pragma unroll
;         for (int j = 0; j < 8; ++j) { const int kidx = 16 * s2 + 8 * (j >> 2) + 4 * hf + (j & 3); tri[s2][j] = (kidx > r) ? (short)0x3F80 : (short)0; }
;     const int nsup = (qb + 1) * 2;
;     const int skey = tid >> 3, sdc = (tid & 7) * 8;
;     u32x4 kreg[2], vreg[2];
;     { const int st0 = (MODE == 0) ? 0 : (nsup - 1);
; #pragma unroll
;       for (int j = 0; j < 2; ++j) { const size_t kr = ((size_t)b * SEQ + st0 * 128 + 64 * j + skey) * NP;
;           kreg[j] = *(const u32x4*)(P + kr + kcol + sdc); vreg[j] = *(const u32x4*)(P + kr + vcol + sdc); } }
.LBB0_246:
	s_xor_b64 s[36:37], s[42:43], -1
	s_and_b64 s[0:1], s[42:43], exec
	s_cselect_b32 s0, s8, s41
	v_lshl_add_u32 v144, s0, 8, v143
	v_or_b32_e32 v146, v144, v119
	v_ashrrev_i32_e32 v147, 31, v146
	v_lshl_add_u64 v[2:3], s[4:5], 0, v[146:147]
	v_mad_u64_u32 v[14:15], s[42:43], v2, s79, v[126:127]
	v_mad_i32_i24 v15, v3, s79, v15
	global_load_dwordx4 v[2:5], v[14:15], off offset:2560
	global_load_dwordx4 v[6:9], v[14:15], off offset:2592
	global_load_dwordx4 v[10:13], v[14:15], off offset:2624
	s_nop 0
	global_load_dwordx4 v[14:17], v[14:15], off offset:2656
	s_lshl_b32 s9, s0, 1
	s_or_b32 s50, s9, 1
	s_lshl_b32 s0, s50, 7
	s_mov_b32 s1, s15
	v_lshl_add_u64 v[210:211], v[120:121], 0, s[0:1]
	v_mad_u64_u32 v[212:213], s[98:99], v210, s79, v[128:129]
	v_mad_i32_i24 v213, v211, s79, v213
	global_load_dwordx4 v[94:97], v[212:213], off offset:3072
	global_load_dwordx4 v[98:101], v[212:213], off offset:3584
	s_or_b32 s100, s0, 64
	s_mov_b32 s101, s15
	v_lshl_add_u64 v[210:211], v[120:121], 0, s[100:101]
	v_mad_u64_u32 v[212:213], s[98:99], v210, s79, v[128:129]
	v_mad_i32_i24 v213, v211, s79, v213
	global_load_dwordx4 v[106:109], v[212:213], off offset:3072
	global_load_dwordx4 v[110:113], v[212:213], off offset:3584
	s_add_i32 s51, s9, 2
	v_mov_b32_e32 v148, 0
	s_waitcnt vmcnt(4)
	v_lshlrev_b32_e32 v21, 16, v5
	s_waitcnt vmcnt(4)
	v_lshlrev_b32_e32 v23, 16, v7
	v_lshlrev_b32_e32 v22, 16, v6
	v_lshlrev_b32_e32 v20, 16, v4
	v_and_b32_e32 v5, 0xffff0000, v5
	v_and_b32_e32 v4, 0xffff0000, v4
	v_and_b32_e32 v7, 0xffff0000, v7
	v_and_b32_e32 v6, 0xffff0000, v6
	v_lshlrev_b32_e32 v25, 16, v9
	v_lshlrev_b32_e32 v24, 16, v8
	v_pk_mul_f32 v[22:23], v[22:23], s[26:27] op_sel_hi:[1,0]
	v_and_b32_e32 v9, 0xffff0000, v9
	v_and_b32_e32 v8, 0xffff0000, v8
	v_pk_mul_f32 v[20:21], v[20:21], s[26:27] op_sel_hi:[1,0]
	v_pk_mul_f32 v[4:5], v[4:5], s[26:27] op_sel_hi:[1,0]
	v_pk_mul_f32 v[6:7], v[6:7], s[26:27] op_sel_hi:[1,0]
	v_pk_mul_f32 v[24:25], v[24:25], s[26:27] op_sel_hi:[1,0]
	v_bfe_u32 v41, v22, 16, 1
	v_bfe_u32 v42, v23, 16, 1
	v_pk_mul_f32 v[8:9], v[8:9], s[26:27] op_sel_hi:[1,0]
	v_bfe_u32 v1, v5, 16, 1
	v_bfe_u32 v36, v21, 16, 1
	v_bfe_u32 v39, v7, 16, 1
	v_bfe_u32 v40, v6, 16, 1
	v_bfe_u32 v43, v24, 16, 1
	v_bfe_u32 v44, v25, 16, 1
	v_add3_u32 v23, v23, v42, s84
	v_add3_u32 v22, v22, v41, s84
	v_bfe_u32 v37, v9, 16, 1
	v_bfe_u32 v38, v8, 16, 1
	v_add3_u32 v1, v5, v1, s84
	v_add3_u32 v5, v21, v36, s84
	v_add3_u32 v6, v6, v40, s84
	v_add3_u32 v7, v7, v39, s84
	v_add3_u32 v21, v25, v44, s84
	v_add3_u32 v24, v24, v43, s84
	v_lshrrev_b32_e32 v22, 16, v22
	v_lshrrev_b32_e32 v23, 16, v23
	v_add3_u32 v8, v8, v38, s84
	v_add3_u32 v9, v9, v37, s84
	v_lshrrev_b32_e32 v24, 16, v24
	v_lshrrev_b32_e32 v21, 16, v21
	v_and_or_b32 v91, v7, s3, v23
	v_and_or_b32 v90, v6, s3, v22
	v_lshl_add_u64 v[6:7], v[120:121], 0, s[0:1]
	v_and_or_b32 v93, v9, s3, v21
	v_and_or_b32 v92, v8, s3, v24
	v_mad_u64_u32 v[8:9], s[42:43], v6, s79, v[128:129]
	s_or_b32 s0, s0, 64
	v_mad_i32_i24 v9, v7, s79, v9
	v_lshl_add_u64 v[6:7], v[120:121], 0, s[0:1]
	v_mad_u64_u32 v[8:9], s[0:1], v6, s79, v[128:129]
	v_mad_i32_i24 v9, v7, s79, v9
	v_lshlrev_b32_e32 v19, 16, v3
	v_lshlrev_b32_e32 v18, 16, v2
	v_and_b32_e32 v3, 0xffff0000, v3
	v_and_b32_e32 v2, 0xffff0000, v2
	v_pk_mul_f32 v[18:19], v[18:19], s[26:27] op_sel_hi:[1,0]
	v_bfe_u32 v35, v20, 16, 1
	v_pk_mul_f32 v[2:3], v[2:3], s[26:27] op_sel_hi:[1,0]
	v_bfe_u32 v30, v4, 16, 1
	v_bfe_u32 v33, v18, 16, 1
	v_bfe_u32 v34, v19, 16, 1
	v_add3_u32 v20, v20, v35, s84
	s_waitcnt vmcnt(5)
; __device__ __forceinline__ u32x4 pack8(const float* f) { u32x4 o; o.x = pk2(f[0], f[1]); o.y = pk2(f[2], f[3]); o.z = pk2(f[4], f[5]); o.w = pk2(f[6], f[7]); return o; }
; template <int MODE>
; __device__ __forceinline__ void attn_unit(const bf16* P, bf16* Y, int b, int h, int qb, unsigned char* lds, int tid) {
;     ...
;     for (int ks = 0; ks < 4; ++ks) { float f[8]; unpack8(*(const u32x4*)(P + rowq * NP + qcol + 16 * ks + 8 * hf), f);
; #pragma unroll
;         for (int i = 0; i < 8; ++i) f[i] *= 0.125f * LOG2E;
;         qf[ks] = __builtin_bit_cast(bf16x8, pack8(f)); }
;     f32x16 o0, o1;
; #pragma unroll
;     for (int i = 0; i < 16; ++i) { o0[i] = 0.f; o1[i] = 0.f; }
;     float m = -INFINITY, lsum = 0.f, carry = 0.f;
	v_lshlrev_b32_e32 v29, 16, v13
	v_lshlrev_b32_e32 v28, 16, v12
	v_and_b32_e32 v13, 0xffff0000, v13
	v_bfe_u32 v31, v3, 16, 1
	v_bfe_u32 v32, v2, 16, 1
	v_add3_u32 v4, v4, v30, s84
	v_add3_u32 v19, v19, v34, s84
	v_add3_u32 v18, v18, v33, s84
	v_lshrrev_b32_e32 v20, 16, v20
	v_lshrrev_b32_e32 v5, 16, v5
	v_and_b32_e32 v12, 0xffff0000, v12
	v_lshlrev_b32_e32 v27, 16, v11
	v_lshlrev_b32_e32 v26, 16, v10
	v_and_b32_e32 v11, 0xffff0000, v11
	v_and_b32_e32 v10, 0xffff0000, v10
	v_add3_u32 v2, v2, v32, s84
	v_add3_u32 v3, v3, v31, s84
	v_lshrrev_b32_e32 v18, 16, v18
	v_lshrrev_b32_e32 v19, 16, v19
	v_and_or_b32 v89, v1, s3, v5
	v_and_or_b32 v88, v4, s3, v20
	v_pk_mul_f32 v[4:5], v[12:13], s[26:27] op_sel_hi:[1,0]
	v_pk_mul_f32 v[26:27], v[26:27], s[26:27] op_sel_hi:[1,0]
	v_pk_mul_f32 v[10:11], v[10:11], s[26:27] op_sel_hi:[1,0]
	v_and_or_b32 v87, v3, s3, v19
	v_and_or_b32 v86, v2, s3, v18
	v_pk_mul_f32 v[2:3], v[28:29], s[26:27] op_sel_hi:[1,0]
	v_bfe_u32 v1, v5, 16, 1
	v_bfe_u32 v6, v4, 16, 1
	v_bfe_u32 v8, v10, 16, 1
	v_add3_u32 v1, v5, v1, s84
	v_bfe_u32 v5, v26, 16, 1
	v_bfe_u32 v9, v2, 16, 1
	v_add3_u32 v8, v10, v8, s84
	v_add3_u32 v4, v4, v6, s84
	v_bfe_u32 v6, v27, 16, 1
	v_bfe_u32 v10, v3, 16, 1
	v_add3_u32 v2, v2, v9, s84
	v_add3_u32 v5, v26, v5, s84
	v_bfe_u32 v7, v11, 16, 1
	v_add3_u32 v3, v3, v10, s84
	v_add3_u32 v6, v27, v6, s84
	v_lshrrev_b32_e32 v5, 16, v5
	v_lshrrev_b32_e32 v2, 16, v2
	v_add3_u32 v7, v11, v7, s84
	v_lshrrev_b32_e32 v6, 16, v6
	v_lshrrev_b32_e32 v3, 16, v3
	v_and_or_b32 v104, v4, s3, v2
	v_and_or_b32 v102, v8, s3, v5
	s_waitcnt vmcnt(4)
	v_and_b32_e32 v5, 0xffff0000, v15
	v_and_b32_e32 v4, 0xffff0000, v14
	v_and_b32_e32 v9, 0xffff0000, v17
	v_and_b32_e32 v8, 0xffff0000, v16
	v_and_or_b32 v105, v1, s3, v3
	v_and_or_b32 v103, v7, s3, v6
	v_lshlrev_b32_e32 v3, 16, v15
	v_lshlrev_b32_e32 v2, 16, v14
	v_pk_mul_f32 v[4:5], v[4:5], s[26:27] op_sel_hi:[1,0]
	v_lshlrev_b32_e32 v7, 16, v17
	v_lshlrev_b32_e32 v6, 16, v16
	v_pk_mul_f32 v[8:9], v[8:9], s[26:27] op_sel_hi:[1,0]
	v_pk_mul_f32 v[2:3], v[2:3], s[26:27] op_sel_hi:[1,0]
	v_pk_mul_f32 v[6:7], v[6:7], s[26:27] op_sel_hi:[1,0]
	v_bfe_u32 v1, v9, 16, 1
	v_bfe_u32 v10, v8, 16, 1
	v_bfe_u32 v11, v5, 16, 1
	v_bfe_u32 v12, v4, 16, 1
	v_add3_u32 v4, v4, v12, s84
	v_add3_u32 v5, v5, v11, s84
	v_add3_u32 v8, v8, v10, s84
	v_add3_u32 v1, v9, v1, s84
	v_bfe_u32 v9, v2, 16, 1
	v_bfe_u32 v10, v3, 16, 1
	v_bfe_u32 v11, v6, 16, 1
	v_bfe_u32 v12, v7, 16, 1
	v_add3_u32 v7, v7, v12, s84
	v_add3_u32 v6, v6, v11, s84
	v_add3_u32 v3, v3, v10, s84
	v_add3_u32 v2, v2, v9, s84
	v_lshrrev_b32_e32 v2, 16, v2
	v_lshrrev_b32_e32 v3, 16, v3
	v_lshrrev_b32_e32 v6, 16, v6
	v_lshrrev_b32_e32 v7, 16, v7
	v_mov_b32_e32 v14, v0
	v_mov_b32_e32 v15, v0
	v_and_or_b32 v117, v1, s3, v7
	v_and_or_b32 v116, v8, s3, v6
	v_and_or_b32 v115, v5, s3, v3
	v_and_or_b32 v114, v4, s3, v2
	v_mov_b32_e32 v1, v0
	v_mov_b32_e32 v2, v0
	v_mov_b32_e32 v3, v0
	v_mov_b32_e32 v4, v0
	v_mov_b32_e32 v5, v0
	v_mov_b32_e32 v6, v0
	v_mov_b32_e32 v7, v0
	v_mov_b32_e32 v8, v0
	v_mov_b32_e32 v9, v0
	v_mov_b32_e32 v10, v0
	v_mov_b32_e32 v11, v0
	v_mov_b32_e32 v12, v0
	v_mov_b32_e32 v13, v0
	v_mov_b64_e32 v[32:33], v[14:15]
	v_mov_b64_e32 v[30:31], v[12:13]
	v_mov_b64_e32 v[28:29], v[10:11]
	v_mov_b64_e32 v[26:27], v[8:9]
	v_mov_b64_e32 v[24:25], v[6:7]
	v_mov_b64_e32 v[22:23], v[4:5]
	v_mov_b64_e32 v[20:21], v[2:3]
	v_mov_b64_e32 v[18:19], v[0:1]
	v_mov_b64_e32 v[16:17], v[14:15]
	s_mov_b32 s1, 0
	v_mov_b64_e32 v[14:15], v[12:13]
	v_mov_b64_e32 v[12:13], v[10:11]
	v_mov_b64_e32 v[10:11], v[8:9]
	v_mov_b64_e32 v[8:9], v[6:7]
	v_mov_b64_e32 v[6:7], v[4:5]
	v_mov_b64_e32 v[4:5], v[2:3]
	v_mov_b64_e32 v[2:3], v[0:1]
	.p2align	6
